# placement pad -8 bytes after fox prologue
# speedup vs baseline: 1.0051x; 1.0051x over previous
; #define GAS __attribute__((address_space(1)))
; template <int MODE> ...
;     ...
;     u32x4 kreg = *(const GAS u32x4*)(kg + (size_t)t_first * 64 * LDH), vreg = *(const GAS u32x4*)(vg + (size_t)t_first * 64 * LDH);
;     float cq = 0.f;
;     if (MODE == 0) {
;         float lf[4];
; #pragma unroll
;         for (int i = 0; i < 4; ++i) { const float x = FL[(rowbase + 4 * tid + i) * 8] + bfv; lf[i] = (fminf(x, 0.f) - __logf(1.f + __expf(-fabsf(x)))) * L2E; }
;         const float s1 = lf[0], s2 = s1 + lf[1], s3 = s2 + lf[2], s4 = s3 + lf[3];
;         float v = s4;
; #pragma unroll
;         for (int off = 1; off < 64; off <<= 1) { const float n = __shfl_up(v, off); if (lane >= off) v += n; }
;         if (lane == 63) wt[wid] = v;
;         __syncthreads();
.LBB0_811:
	v_readlane_b32 s2, v254, 8
	s_mul_i32 s0, s2, 0x2aab
	s_lshr_b32 s1, s0, 31
	s_lshr_b32 s0, s0, 16
	s_add_i32 s0, s0, s1
	s_mul_i32 s1, s0, 6
	s_sub_i32 s4, s2, s1
	s_sext_i32_i16 s1, s4
	s_bfe_i64 s[4:5], s[4:5], 0x100000
	s_lshl_b32 s2, s1, 6
	s_lshl_b64 s[4:5], s[4:5], 2
	v_readlane_b32 s1, v252, 58
	s_add_u32 s8, s1, s4
	v_readlane_b32 s1, v252, 59
	s_addc_u32 s9, s1, s5
	s_add_u32 s4, s23, s4
	v_readlane_b32 s1, v252, 55
	s_addc_u32 s5, s1, s5
	v_mov_b32_e32 v1, v230
	global_load_dword v19, v0, s[4:5]
	s_ashr_i32 s3, s2, 31
	v_readfirstlane_b32 s1, v1
	s_ashr_i32 s6, s1, 6
	s_bfe_i64 s[0:1], s[0:1], 0x100000
	s_lshl_b64 s[4:5], s[0:1], 11
	v_readlane_b32 s0, v252, 56
	v_ashrrev_i32_e32 v18, 3, v1
	v_readlane_b32 s1, v252, 57
	v_add_u32_e32 v4, s4, v18
	v_lshlrev_b32_e32 v12, 2, v1
	v_mov_b64_e32 v[2:3], s[0:1]
	s_movk_i32 s0, 0x1880
	v_mad_i64_i32 v[2:3], s[0:1], v4, s0, v[2:3]
	v_lshlrev_b32_e32 v4, 3, v1
	v_ashrrev_i32_e32 v13, 31, v12
	v_and_b32_e32 v4, 56, v4
	v_lshl_add_u64 v[14:15], s[4:5], 0, v[12:13]
	v_lshl_add_u64 v[2:3], s[2:3], 1, v[2:3]
	v_lshlrev_b32_e32 v10, 1, v4
	v_mov_b32_e32 v11, v0
	v_lshlrev_b64 v[14:15], 5, v[14:15]
	v_lshl_add_u64 v[98:99], v[2:3], 0, v[10:11]
	v_lshl_add_u64 v[16:17], s[8:9], 0, v[14:15]
	global_load_dwordx4 v[2:5], v[98:99], off offset:768
	global_load_dwordx4 v[6:9], v[98:99], off offset:1536
	global_load_dword v11, v[16:17], off
	global_load_dword v176, v[16:17], off offset:32
	global_load_dword v177, v[16:17], off offset:64
	global_load_dword v179, v[16:17], off offset:96
	s_mov_b32 s8, 0xbfb8aa3b
	s_mov_b32 s7, 0x800000
	s_mov_b32 s9, 0x3f317217
	s_mov_b32 s10, 0x7f800000
	v_mov_b32_e32 v21, 0x41b17218
	s_waitcnt vmcnt(0)
	v_add_f32_e32 v11, v19, v11
	v_min_f32_e32 v13, 0, v11
	v_mul_f32_e64 v11, |v11|, s8
	v_exp_f32_e32 v11, v11
	s_nop 0
	v_add_f32_e32 v11, 1.0, v11
	v_cmp_gt_f32_e32 vcc, s7, v11
	s_nop 1
	v_cndmask_b32_e64 v14, 0, 32, vcc
	v_ldexp_f32 v11, v11, v14
	v_log_f32_e32 v11, v11
	s_nop 0
	v_mul_f32_e32 v14, 0x3f317217, v11
	v_fma_f32 v14, v11, s9, -v14
	v_fmac_f32_e32 v14, 0x3377d1cf, v11
	v_fmac_f32_e32 v14, 0x3f317217, v11
	v_cmp_lt_f32_e64 s[0:1], |v11|, s10
	s_nop 1
	v_cndmask_b32_e64 v11, v11, v14, s[0:1]
	v_cndmask_b32_e32 v14, 0, v21, vcc
	v_sub_f32_e32 v11, v11, v14
	v_sub_f32_e32 v11, v13, v11
	v_mul_f32_e32 v14, 0x3fb8aa3b, v11
	v_add_f32_e32 v11, v19, v176
	v_min_f32_e32 v13, 0, v11
	v_mul_f32_e64 v11, |v11|, s8
	v_exp_f32_e32 v11, v11
	s_nop 0
	v_add_f32_e32 v11, 1.0, v11
	v_cmp_gt_f32_e32 vcc, s7, v11
	s_nop 1
	v_cndmask_b32_e64 v15, 0, 32, vcc
	v_ldexp_f32 v11, v11, v15
	v_log_f32_e32 v11, v11
	s_nop 0
	v_mul_f32_e32 v15, 0x3f317217, v11
	v_fma_f32 v15, v11, s9, -v15
	v_fmac_f32_e32 v15, 0x3377d1cf, v11
	v_fmac_f32_e32 v15, 0x3f317217, v11
	v_cmp_lt_f32_e64 s[0:1], |v11|, s10
	s_nop 1
	v_cndmask_b32_e64 v11, v11, v15, s[0:1]
	v_cndmask_b32_e32 v15, 0, v21, vcc
	v_sub_f32_e32 v11, v11, v15
	v_sub_f32_e32 v13, v13, v11
	v_add_f32_e32 v11, v19, v177
	v_min_f32_e32 v15, 0, v11
	v_mul_f32_e64 v11, |v11|, s8
	v_exp_f32_e32 v11, v11
	s_nop 0
	v_add_f32_e32 v11, 1.0, v11
	v_cmp_gt_f32_e32 vcc, s7, v11
	s_nop 1
	v_cndmask_b32_e64 v20, 0, 32, vcc
	v_ldexp_f32 v11, v11, v20
	v_log_f32_e32 v11, v11
	s_nop 0
	v_mul_f32_e32 v20, 0x3f317217, v11
	v_fma_f32 v20, v11, s9, -v20
	v_fmac_f32_e32 v20, 0x3377d1cf, v11
	v_fmac_f32_e32 v20, 0x3f317217, v11
	v_cmp_lt_f32_e64 s[0:1], |v11|, s10
	s_nop 1
	v_cndmask_b32_e64 v11, v11, v20, s[0:1]
	v_cndmask_b32_e32 v20, 0, v21, vcc
	v_sub_f32_e32 v11, v11, v20
	v_sub_f32_e32 v20, v15, v11
	v_add_f32_e32 v11, v19, v179
	s_nop 0
	v_min_f32_e32 v15, 0, v11
	v_mul_f32_e64 v11, |v11|, s8
	v_exp_f32_e32 v11, v11
	v_add_u32_e32 v19, -1, v224
	v_add_f32_e32 v11, 1.0, v11
	v_cmp_gt_f32_e32 vcc, s7, v11
	s_nop 1
	v_cndmask_b32_e64 v16, 0, 32, vcc
	v_ldexp_f32 v11, v11, v16
	v_log_f32_e32 v11, v11
	s_nop 0
	v_mul_f32_e32 v16, 0x3f317217, v11
	v_fma_f32 v16, v11, s9, -v16
	v_fmac_f32_e32 v16, 0x3377d1cf, v11
	v_fmac_f32_e32 v16, 0x3f317217, v11
	v_cmp_lt_f32_e64 s[0:1], |v11|, s10
	s_nop 1
	v_cndmask_b32_e64 v11, v11, v16, s[0:1]
	v_cndmask_b32_e32 v16, 0, v21, vcc
	v_sub_f32_e32 v11, v11, v16
	v_sub_f32_e32 v17, v15, v11
	v_fmamk_f32 v15, v13, 0x3fb8aa3b, v14
	v_and_b32_e32 v13, 64, v224
	v_cmp_lt_i32_e32 vcc, v19, v13
	v_fmamk_f32 v16, v20, 0x3fb8aa3b, v15
	v_fmamk_f32 v17, v17, 0x3fb8aa3b, v16
	v_cndmask_b32_e32 v19, v19, v224, vcc
	v_lshlrev_b32_e32 v19, 2, v19
	ds_bpermute_b32 v19, v19, v17
	v_and_b32_e32 v11, 63, v1
	v_cmp_eq_u32_e32 vcc, 0, v11
	v_add_u32_e32 v20, -2, v224
	s_waitcnt lgkmcnt(0)
	v_add_f32_e32 v19, v17, v19
	v_cndmask_b32_e32 v19, v19, v17, vcc
	v_cmp_lt_i32_e32 vcc, v20, v13
	s_nop 1
	v_cndmask_b32_e32 v20, v20, v224, vcc
	v_lshlrev_b32_e32 v20, 2, v20
	ds_bpermute_b32 v20, v20, v19
	v_cmp_gt_u32_e32 vcc, 2, v11
	s_waitcnt lgkmcnt(0)
	v_add_f32_e32 v20, v19, v20
	v_cndmask_b32_e32 v19, v20, v19, vcc
	v_add_u32_e32 v20, -4, v224
	v_cmp_lt_i32_e32 vcc, v20, v13
	s_nop 1
	v_cndmask_b32_e32 v20, v20, v224, vcc
	v_lshlrev_b32_e32 v20, 2, v20
	ds_bpermute_b32 v20, v20, v19
	v_cmp_gt_u32_e32 vcc, 4, v11
	s_waitcnt lgkmcnt(0)
	v_add_f32_e32 v20, v19, v20
	v_cndmask_b32_e32 v19, v20, v19, vcc
	v_add_u32_e32 v20, -8, v224
	v_cmp_lt_i32_e32 vcc, v20, v13
	s_nop 1
	v_cndmask_b32_e32 v20, v20, v224, vcc
	v_lshlrev_b32_e32 v20, 2, v20
	ds_bpermute_b32 v20, v20, v19
	v_cmp_gt_u32_e32 vcc, 8, v11
	s_waitcnt lgkmcnt(0)
	v_add_f32_e32 v20, v19, v20
	v_cndmask_b32_e32 v19, v20, v19, vcc
	v_add_u32_e32 v20, -16, v224
	v_cmp_lt_i32_e32 vcc, v20, v13
	s_nop 1
	v_cndmask_b32_e32 v20, v20, v224, vcc
	v_lshlrev_b32_e32 v20, 2, v20
	ds_bpermute_b32 v20, v20, v19
	v_cmp_gt_u32_e32 vcc, 16, v11
	s_waitcnt lgkmcnt(0)
	v_add_f32_e32 v20, v19, v20
	v_cndmask_b32_e32 v19, v20, v19, vcc
	v_subrev_u32_e32 v20, 32, v224
	v_cmp_lt_i32_e32 vcc, v20, v13
	s_nop 1
	v_cndmask_b32_e32 v20, v20, v224, vcc
	v_lshlrev_b32_e32 v20, 2, v20
	ds_bpermute_b32 v20, v20, v19
	v_cmp_eq_u32_e32 vcc, 63, v11
	s_waitcnt lgkmcnt(0)
	v_add_f32_e32 v20, v19, v20
	s_and_saveexec_b64 s[0:1], vcc
	s_lshl_b32 s7, s6, 2
	s_add_i32 s7, s7, 0
	v_mov_b32_e32 v21, s7
	ds_write_b32 v21, v20 offset:45056
	s_or_b64 exec, exec, s[0:1]
	s_cmp_lt_i32 s6, 1
	s_waitcnt lgkmcnt(0)
	s_barrier
	s_cbranch_scc1 .LBB0_860
	ds_read_b32 v21, v0 offset:45056
	s_waitcnt lgkmcnt(0)
	v_add_f32_e32 v21, 0, v21
	s_cmp_lt_i32 s6, 2
	s_cbranch_scc1 .LBB0_816
